# SwiGLU HALFM tail K-loop also on the 3-buffer 2-barrier schedule; K-tile 0 peeled with srcC=0 in both tails
# speedup vs baseline: 1.0129x; 1.0129x over previous
.LBB0_267:
	v_or_b32_e32 v82, s8, v1
	v_and_b32_e32 v66, 63, v16
	v_lshlrev_b32_e32 v3, 6, v82
	s_movk_i32 s0, 0x3c0
	v_lshlrev_b32_e32 v16, 2, v82
	v_and_or_b32 v3, v3, s0, v18
	s_lshl_b32 s0, s3, 13
	v_and_b32_e32 v16, 32, v16
	v_bitop3_b32 v16, v3, s0, v16 bitop3:0xde
	v_lshl_or_b32 v3, v1, 6, v18
	s_lshl_b32 s0, s14, 12
	v_and_b32_e32 v2, 32, v2
	v_bitop3_b32 v67, v3, s0, v2 bitop3:0xde
	s_add_i32 m0, s35, 0x18000
	v_lshl_add_u64 v[2:3], v[10:11], 0, s[76:77]
	s_lshl_b32 s21, s14, 5
	s_waitcnt vmcnt(2)
	s_barrier
	global_load_lds_dwordx4 v[2:3], off
	v_lshl_add_u64 v[2:3], v[8:9], 0, s[76:77]
	s_add_i32 m0, s35, 0x1a000
	s_add_i32 s37, s35, 0x8000
	s_add_i32 s38, s35, 0xa000
	global_load_lds_dwordx4 v[2:3], off
	v_lshl_add_u64 v[2:3], v[6:7], 0, s[76:77]
	s_mov_b32 m0, s37
	s_add_u32 s8, s4, 0x40080
	global_load_lds_dwordx4 v[2:3], off
	v_lshl_add_u64 v[2:3], v[4:5], 0, s[76:77]
	s_mov_b32 m0, s38
	s_addc_u32 s9, s5, 0
	global_load_lds_dwordx4 v[2:3], off
	s_add_i32 m0, s35, 0x1c000
	v_lshl_add_u64 v[2:3], s[8:9], 0, v[50:51]
	global_load_lds_dwordx4 v[2:3], off
	v_lshl_add_u64 v[2:3], s[8:9], 0, v[46:47]
	s_add_i32 m0, s35, 0x1e000
	v_readlane_b32 s0, v254, 53
	global_load_lds_dwordx4 v[2:3], off
	v_lshlrev_b32_e32 v2, 14, v12
	v_and_b32_e32 v2, 0xffff8000, v2
	v_lshl_add_u32 v2, v13, 11, v2
	v_and_b32_e32 v3, 1, v12
	s_add_u32 s8, s26, s0
	v_lshl_or_b32 v2, v3, 6, v2
	s_addc_u32 s9, s1, 0
	v_lshl_add_u32 v2, v14, 1, v2
	v_mov_b32_e32 v3, v0
	v_lshl_add_u64 v[62:63], s[8:9], 0, v[2:3]
	v_lshlrev_b32_e32 v2, 14, v17
	v_and_b32_e32 v2, 0xffff8000, v2
	v_lshl_add_u32 v2, v15, 11, v2
	v_and_b32_e32 v3, 1, v17
	v_readlane_b32 s0, v254, 52
	v_lshl_or_b32 v2, v3, 6, v2
	s_add_u32 s40, s26, s0
	v_lshl_add_u32 v2, v19, 1, v2
	v_mov_b32_e32 v3, v0
	s_addc_u32 s41, s1, 0
	v_readlane_b32 s0, v254, 54
	v_lshl_add_u64 v[64:65], s[8:9], 0, v[2:3]
	s_add_u32 s0, s26, s0
	v_readlane_b32 s8, v254, 55
	s_addc_u32 s8, s1, s8
	s_add_u32 s1, s27, s30
	s_waitcnt vmcnt(6)
	s_addc_u32 s9, 0, 0
	s_add_u32 s1, s0, s1
	s_addc_u32 s26, s8, s9
	s_mov_b32 s27, -2
	s_mov_b64 s[8:9], 0
	v_add_u32_e32 v68, 0, v16
	s_barrier
	s_movk_i32 s8, 0x100
	s_movk_i32 s9, 0x800
	s_mov_b32 s27, 0
	v_add_u32_e32 v156, 0x10000, v67
	v_add_u32_e32 v157, 0x21c00, v67
	s_add_u32 s10, s4, s8
	s_addc_u32 s11, s5, 0
	s_add_u32 s12, s10, 0x40000
	s_addc_u32 s13, s11, 0
	s_add_u32 s42, s6, s8
	s_addc_u32 s43, s7, 0
	s_addk_i32 s8, 0x80
	s_cmp_eq_u32 s8, s9
	s_cselect_b32 s8, 0, s8
	s_add_i32 m0, s35, 0xc000
	ds_read_b128 v[84:87], v156 offset:0
	ds_read_b128 v[88:91], v156 offset:1024
	ds_read_b128 v[92:95], v156 offset:2048
	ds_read_b128 v[96:99], v156 offset:3072
	global_load_lds_dwordx4 v50, s[10:11]
	s_add_i32 m0, s35, 0xe000
	ds_read_b128 v[116:119], v68 offset:0
	ds_read_b128 v[120:123], v68 offset:1024
	ds_read_b128 v[124:127], v68 offset:2048
	global_load_lds_dwordx4 v46, s[10:11]
	s_add_i32 m0, s35, 0x21c00
	ds_read_b128 v[128:131], v68 offset:3072
	ds_read_b128 v[132:135], v68 offset:4096
	ds_read_b128 v[136:139], v68 offset:5120
	global_load_lds_dwordx4 v50, s[12:13]
	s_add_i32 m0, s35, 0x23c00
	ds_read_b128 v[140:143], v68 offset:6144
	ds_read_b128 v[144:147], v68 offset:7168
	global_load_lds_dwordx4 v46, s[12:13]
	s_add_i32 m0, s35, 0x4000
	ds_read_b128 v[100:103], v156 offset:16384
	ds_read_b128 v[104:107], v156 offset:17408
	global_load_lds_dwordx4 v52, s[42:43]
	s_add_i32 m0, s35, 0x6000
	ds_read_b128 v[108:111], v156 offset:18432
	ds_read_b128 v[112:115], v156 offset:19456
	global_load_lds_dwordx4 v48, s[42:43]
	s_waitcnt vmcnt(6)
	s_waitcnt lgkmcnt(0)
	s_barrier
	s_setprio 1
	v_mfma_f32_16x16x32_bf16 v[78:81], v[84:87], v[116:119], 0
	v_mfma_f32_16x16x32_bf16 v[70:73], v[92:95], v[116:119], 0
	v_mfma_f32_16x16x32_bf16 v[54:57], v[84:87], v[124:127], 0
	s_add_u32 s10, s4, s8
	v_mfma_f32_16x16x32_bf16 v[38:41], v[92:95], v[124:127], 0
	s_addc_u32 s11, s5, 0
	v_mfma_f32_16x16x32_bf16 v[30:33], v[84:87], v[132:135], 0
	s_add_u32 s12, s10, 0x40000
	v_mfma_f32_16x16x32_bf16 v[22:25], v[92:95], v[132:135], 0
	s_addc_u32 s13, s11, 0
	v_mfma_f32_16x16x32_bf16 v[14:17], v[84:87], v[140:143], 0
	s_add_u32 s42, s6, s8
	v_mfma_f32_16x16x32_bf16 v[6:9], v[92:95], v[140:143], 0
	s_addc_u32 s43, s7, 0
	v_mfma_f32_16x16x32_bf16 v[78:81], v[88:91], v[120:123], v[78:81]
	s_addk_i32 s8, 0x80
	v_mfma_f32_16x16x32_bf16 v[70:73], v[96:99], v[120:123], v[70:73]
	s_cmp_eq_u32 s8, s9
	v_mfma_f32_16x16x32_bf16 v[54:57], v[88:91], v[128:131], v[54:57]
	s_cselect_b32 s8, 0, s8
	v_mfma_f32_16x16x32_bf16 v[38:41], v[96:99], v[128:131], v[38:41]
	v_mfma_f32_16x16x32_bf16 v[30:33], v[88:91], v[136:139], v[30:33]
	v_mfma_f32_16x16x32_bf16 v[22:25], v[96:99], v[136:139], v[22:25]
	v_mfma_f32_16x16x32_bf16 v[14:17], v[88:91], v[144:147], v[14:17]
	v_mfma_f32_16x16x32_bf16 v[6:9], v[96:99], v[144:147], v[6:9]
	v_mfma_f32_16x16x32_bf16 v[74:77], v[100:103], v[116:119], 0
	v_mfma_f32_16x16x32_bf16 v[58:61], v[108:111], v[116:119], 0
	v_mfma_f32_16x16x32_bf16 v[42:45], v[100:103], v[124:127], 0
	v_mfma_f32_16x16x32_bf16 v[34:37], v[108:111], v[124:127], 0
	v_mfma_f32_16x16x32_bf16 v[26:29], v[100:103], v[132:135], 0
	v_mfma_f32_16x16x32_bf16 v[18:21], v[108:111], v[132:135], 0
	v_mfma_f32_16x16x32_bf16 v[10:13], v[100:103], v[140:143], 0
	v_mfma_f32_16x16x32_bf16 v[2:5], v[108:111], v[140:143], 0
	v_mfma_f32_16x16x32_bf16 v[74:77], v[104:107], v[120:123], v[74:77]
	v_mfma_f32_16x16x32_bf16 v[58:61], v[112:115], v[120:123], v[58:61]
	v_mfma_f32_16x16x32_bf16 v[42:45], v[104:107], v[128:131], v[42:45]
	v_mfma_f32_16x16x32_bf16 v[34:37], v[112:115], v[128:131], v[34:37]
	v_mfma_f32_16x16x32_bf16 v[26:29], v[104:107], v[136:139], v[26:29]
	v_mfma_f32_16x16x32_bf16 v[18:21], v[112:115], v[136:139], v[18:21]
	v_mfma_f32_16x16x32_bf16 v[10:13], v[104:107], v[144:147], v[10:13]
	v_mfma_f32_16x16x32_bf16 v[2:5], v[112:115], v[144:147], v[2:5]
	s_setprio 0
	s_barrier
	s_add_i32 s27, s27, 1
.LBB0_268:
	s_add_i32 m0, s35, 0x10000
	ds_read_b128 v[84:87], v156 offset:32768
	ds_read_b128 v[88:91], v156 offset:33792
	ds_read_b128 v[92:95], v156 offset:34816
	ds_read_b128 v[96:99], v156 offset:35840
	global_load_lds_dwordx4 v50, s[10:11]
	s_add_i32 m0, s35, 0x12000
	ds_read_b128 v[116:119], v68 offset:32768
	ds_read_b128 v[120:123], v68 offset:33792
	ds_read_b128 v[124:127], v68 offset:34816
	global_load_lds_dwordx4 v46, s[10:11]
	s_add_i32 m0, s35, 0x14000
	ds_read_b128 v[128:131], v68 offset:35840
	ds_read_b128 v[132:135], v68 offset:36864
	ds_read_b128 v[136:139], v68 offset:37888
	global_load_lds_dwordx4 v50, s[12:13]
	s_add_i32 m0, s35, 0x16000
	ds_read_b128 v[140:143], v68 offset:38912
	ds_read_b128 v[144:147], v68 offset:39936
	global_load_lds_dwordx4 v46, s[12:13]
	s_add_i32 m0, s35, 0x0
	ds_read_b128 v[100:103], v156 offset:49152
	ds_read_b128 v[104:107], v156 offset:50176
	global_load_lds_dwordx4 v52, s[42:43]
	s_add_i32 m0, s35, 0x2000
	ds_read_b128 v[108:111], v156 offset:51200
	ds_read_b128 v[112:115], v156 offset:52224
	global_load_lds_dwordx4 v48, s[42:43]
	s_waitcnt vmcnt(6)
	s_waitcnt lgkmcnt(0)
	s_barrier
	s_setprio 1
	v_mfma_f32_16x16x32_bf16 v[78:81], v[84:87], v[116:119], v[78:81]
	v_mfma_f32_16x16x32_bf16 v[70:73], v[92:95], v[116:119], v[70:73]
	v_mfma_f32_16x16x32_bf16 v[54:57], v[84:87], v[124:127], v[54:57]
	s_add_u32 s10, s4, s8
	v_mfma_f32_16x16x32_bf16 v[38:41], v[92:95], v[124:127], v[38:41]
	s_addc_u32 s11, s5, 0
	v_mfma_f32_16x16x32_bf16 v[30:33], v[84:87], v[132:135], v[30:33]
	s_add_u32 s12, s10, 0x40000
	v_mfma_f32_16x16x32_bf16 v[22:25], v[92:95], v[132:135], v[22:25]
	s_addc_u32 s13, s11, 0
	v_mfma_f32_16x16x32_bf16 v[14:17], v[84:87], v[140:143], v[14:17]
	s_add_u32 s42, s6, s8
	v_mfma_f32_16x16x32_bf16 v[6:9], v[92:95], v[140:143], v[6:9]
	s_addc_u32 s43, s7, 0
	v_mfma_f32_16x16x32_bf16 v[78:81], v[88:91], v[120:123], v[78:81]
	s_addk_i32 s8, 0x80
	v_mfma_f32_16x16x32_bf16 v[70:73], v[96:99], v[120:123], v[70:73]
	s_cmp_eq_u32 s8, s9
	v_mfma_f32_16x16x32_bf16 v[54:57], v[88:91], v[128:131], v[54:57]
	s_cselect_b32 s8, 0, s8
	v_mfma_f32_16x16x32_bf16 v[38:41], v[96:99], v[128:131], v[38:41]
	v_mfma_f32_16x16x32_bf16 v[30:33], v[88:91], v[136:139], v[30:33]
	v_mfma_f32_16x16x32_bf16 v[22:25], v[96:99], v[136:139], v[22:25]
	v_mfma_f32_16x16x32_bf16 v[14:17], v[88:91], v[144:147], v[14:17]
	v_mfma_f32_16x16x32_bf16 v[6:9], v[96:99], v[144:147], v[6:9]
	v_mfma_f32_16x16x32_bf16 v[74:77], v[100:103], v[116:119], v[74:77]
	v_mfma_f32_16x16x32_bf16 v[58:61], v[108:111], v[116:119], v[58:61]
	v_mfma_f32_16x16x32_bf16 v[42:45], v[100:103], v[124:127], v[42:45]
	v_mfma_f32_16x16x32_bf16 v[34:37], v[108:111], v[124:127], v[34:37]
	v_mfma_f32_16x16x32_bf16 v[26:29], v[100:103], v[132:135], v[26:29]
	v_mfma_f32_16x16x32_bf16 v[18:21], v[108:111], v[132:135], v[18:21]
	v_mfma_f32_16x16x32_bf16 v[10:13], v[100:103], v[140:143], v[10:13]
	v_mfma_f32_16x16x32_bf16 v[2:5], v[108:111], v[140:143], v[2:5]
	v_mfma_f32_16x16x32_bf16 v[74:77], v[104:107], v[120:123], v[74:77]
	v_mfma_f32_16x16x32_bf16 v[58:61], v[112:115], v[120:123], v[58:61]
	v_mfma_f32_16x16x32_bf16 v[42:45], v[104:107], v[128:131], v[42:45]
	v_mfma_f32_16x16x32_bf16 v[34:37], v[112:115], v[128:131], v[34:37]
	v_mfma_f32_16x16x32_bf16 v[26:29], v[104:107], v[136:139], v[26:29]
	v_mfma_f32_16x16x32_bf16 v[18:21], v[112:115], v[136:139], v[18:21]
	v_mfma_f32_16x16x32_bf16 v[10:13], v[104:107], v[144:147], v[10:13]
	v_mfma_f32_16x16x32_bf16 v[2:5], v[112:115], v[144:147], v[2:5]
	s_setprio 0
	s_barrier
	s_add_i32 s27, s27, 1
	s_cmp_ge_u32 s27, 16
	s_cbranch_scc1 .Lst_done
	s_add_i32 m0, s35, 0x18000
	ds_read_b128 v[84:87], v67 offset:49152
	ds_read_b128 v[88:91], v67 offset:50176
	ds_read_b128 v[92:95], v67 offset:51200
	ds_read_b128 v[96:99], v67 offset:52224
	global_load_lds_dwordx4 v50, s[10:11]
	s_add_i32 m0, s35, 0x1a000
	ds_read_b128 v[116:119], v68 offset:16384
	ds_read_b128 v[120:123], v68 offset:17408
	ds_read_b128 v[124:127], v68 offset:18432
	global_load_lds_dwordx4 v46, s[10:11]
	s_add_i32 m0, s35, 0x1c000
	ds_read_b128 v[128:131], v68 offset:19456
	ds_read_b128 v[132:135], v68 offset:20480
	ds_read_b128 v[136:139], v68 offset:21504
	global_load_lds_dwordx4 v50, s[12:13]
	s_add_i32 m0, s35, 0x1e000
	ds_read_b128 v[140:143], v68 offset:22528
	ds_read_b128 v[144:147], v68 offset:23552
	global_load_lds_dwordx4 v46, s[12:13]
	s_add_i32 m0, s35, 0x8000
	ds_read_b128 v[100:103], v157 offset:0
	ds_read_b128 v[104:107], v157 offset:1024
	global_load_lds_dwordx4 v52, s[42:43]
	s_add_i32 m0, s35, 0xa000
	ds_read_b128 v[108:111], v157 offset:2048
	ds_read_b128 v[112:115], v157 offset:3072
	global_load_lds_dwordx4 v48, s[42:43]
	s_waitcnt vmcnt(6)
	s_waitcnt lgkmcnt(0)
	s_barrier
	s_setprio 1
	v_mfma_f32_16x16x32_bf16 v[78:81], v[84:87], v[116:119], v[78:81]
	v_mfma_f32_16x16x32_bf16 v[70:73], v[92:95], v[116:119], v[70:73]
	v_mfma_f32_16x16x32_bf16 v[54:57], v[84:87], v[124:127], v[54:57]
	s_add_u32 s10, s4, s8
	v_mfma_f32_16x16x32_bf16 v[38:41], v[92:95], v[124:127], v[38:41]
	s_addc_u32 s11, s5, 0
	v_mfma_f32_16x16x32_bf16 v[30:33], v[84:87], v[132:135], v[30:33]
	s_add_u32 s12, s10, 0x40000
	v_mfma_f32_16x16x32_bf16 v[22:25], v[92:95], v[132:135], v[22:25]
	s_addc_u32 s13, s11, 0
	v_mfma_f32_16x16x32_bf16 v[14:17], v[84:87], v[140:143], v[14:17]
	s_add_u32 s42, s6, s8
	v_mfma_f32_16x16x32_bf16 v[6:9], v[92:95], v[140:143], v[6:9]
	s_addc_u32 s43, s7, 0
	v_mfma_f32_16x16x32_bf16 v[78:81], v[88:91], v[120:123], v[78:81]
	s_addk_i32 s8, 0x80
	v_mfma_f32_16x16x32_bf16 v[70:73], v[96:99], v[120:123], v[70:73]
	s_cmp_eq_u32 s8, s9
	v_mfma_f32_16x16x32_bf16 v[54:57], v[88:91], v[128:131], v[54:57]
	s_cselect_b32 s8, 0, s8
	v_mfma_f32_16x16x32_bf16 v[38:41], v[96:99], v[128:131], v[38:41]
	v_mfma_f32_16x16x32_bf16 v[30:33], v[88:91], v[136:139], v[30:33]
	v_mfma_f32_16x16x32_bf16 v[22:25], v[96:99], v[136:139], v[22:25]
	v_mfma_f32_16x16x32_bf16 v[14:17], v[88:91], v[144:147], v[14:17]
	v_mfma_f32_16x16x32_bf16 v[6:9], v[96:99], v[144:147], v[6:9]
	v_mfma_f32_16x16x32_bf16 v[74:77], v[100:103], v[116:119], v[74:77]
	v_mfma_f32_16x16x32_bf16 v[58:61], v[108:111], v[116:119], v[58:61]
	v_mfma_f32_16x16x32_bf16 v[42:45], v[100:103], v[124:127], v[42:45]
	v_mfma_f32_16x16x32_bf16 v[34:37], v[108:111], v[124:127], v[34:37]
	v_mfma_f32_16x16x32_bf16 v[26:29], v[100:103], v[132:135], v[26:29]
	v_mfma_f32_16x16x32_bf16 v[18:21], v[108:111], v[132:135], v[18:21]
	v_mfma_f32_16x16x32_bf16 v[10:13], v[100:103], v[140:143], v[10:13]
	v_mfma_f32_16x16x32_bf16 v[2:5], v[108:111], v[140:143], v[2:5]
	v_mfma_f32_16x16x32_bf16 v[74:77], v[104:107], v[120:123], v[74:77]
	v_mfma_f32_16x16x32_bf16 v[58:61], v[112:115], v[120:123], v[58:61]
	v_mfma_f32_16x16x32_bf16 v[42:45], v[104:107], v[128:131], v[42:45]
	v_mfma_f32_16x16x32_bf16 v[34:37], v[112:115], v[128:131], v[34:37]
	v_mfma_f32_16x16x32_bf16 v[26:29], v[104:107], v[136:139], v[26:29]
	v_mfma_f32_16x16x32_bf16 v[18:21], v[112:115], v[136:139], v[18:21]
	v_mfma_f32_16x16x32_bf16 v[10:13], v[104:107], v[144:147], v[10:13]
	v_mfma_f32_16x16x32_bf16 v[2:5], v[112:115], v[144:147], v[2:5]
	s_setprio 0
	s_barrier
	s_add_i32 s27, s27, 1
	s_cmp_ge_u32 s27, 16
	s_cbranch_scc1 .Lst_done
	s_add_i32 m0, s35, 0xc000
	ds_read_b128 v[84:87], v156 offset:0
	ds_read_b128 v[88:91], v156 offset:1024
	ds_read_b128 v[92:95], v156 offset:2048
	ds_read_b128 v[96:99], v156 offset:3072
	global_load_lds_dwordx4 v50, s[10:11]
	s_add_i32 m0, s35, 0xe000
	ds_read_b128 v[116:119], v68 offset:0
	ds_read_b128 v[120:123], v68 offset:1024
	ds_read_b128 v[124:127], v68 offset:2048
	global_load_lds_dwordx4 v46, s[10:11]
	s_add_i32 m0, s35, 0x21c00
	ds_read_b128 v[128:131], v68 offset:3072
	ds_read_b128 v[132:135], v68 offset:4096
	ds_read_b128 v[136:139], v68 offset:5120
	global_load_lds_dwordx4 v50, s[12:13]
	s_add_i32 m0, s35, 0x23c00
	ds_read_b128 v[140:143], v68 offset:6144
	ds_read_b128 v[144:147], v68 offset:7168
	global_load_lds_dwordx4 v46, s[12:13]
	s_add_i32 m0, s35, 0x4000
	ds_read_b128 v[100:103], v156 offset:16384
	ds_read_b128 v[104:107], v156 offset:17408
	global_load_lds_dwordx4 v52, s[42:43]
	s_add_i32 m0, s35, 0x6000
	ds_read_b128 v[108:111], v156 offset:18432
	ds_read_b128 v[112:115], v156 offset:19456
	global_load_lds_dwordx4 v48, s[42:43]
	s_waitcnt vmcnt(6)
	s_waitcnt lgkmcnt(0)
	s_barrier
	s_setprio 1
	v_mfma_f32_16x16x32_bf16 v[78:81], v[84:87], v[116:119], v[78:81]
	v_mfma_f32_16x16x32_bf16 v[70:73], v[92:95], v[116:119], v[70:73]
	v_mfma_f32_16x16x32_bf16 v[54:57], v[84:87], v[124:127], v[54:57]
	s_add_u32 s10, s4, s8
	v_mfma_f32_16x16x32_bf16 v[38:41], v[92:95], v[124:127], v[38:41]
	s_addc_u32 s11, s5, 0
	v_mfma_f32_16x16x32_bf16 v[30:33], v[84:87], v[132:135], v[30:33]
	s_add_u32 s12, s10, 0x40000
	v_mfma_f32_16x16x32_bf16 v[22:25], v[92:95], v[132:135], v[22:25]
	s_addc_u32 s13, s11, 0
	v_mfma_f32_16x16x32_bf16 v[14:17], v[84:87], v[140:143], v[14:17]
	s_add_u32 s42, s6, s8
	v_mfma_f32_16x16x32_bf16 v[6:9], v[92:95], v[140:143], v[6:9]
	s_addc_u32 s43, s7, 0
	v_mfma_f32_16x16x32_bf16 v[78:81], v[88:91], v[120:123], v[78:81]
	s_addk_i32 s8, 0x80
	v_mfma_f32_16x16x32_bf16 v[70:73], v[96:99], v[120:123], v[70:73]
	s_cmp_eq_u32 s8, s9
	v_mfma_f32_16x16x32_bf16 v[54:57], v[88:91], v[128:131], v[54:57]
	s_cselect_b32 s8, 0, s8
	v_mfma_f32_16x16x32_bf16 v[38:41], v[96:99], v[128:131], v[38:41]
	v_mfma_f32_16x16x32_bf16 v[30:33], v[88:91], v[136:139], v[30:33]
	v_mfma_f32_16x16x32_bf16 v[22:25], v[96:99], v[136:139], v[22:25]
	v_mfma_f32_16x16x32_bf16 v[14:17], v[88:91], v[144:147], v[14:17]
	v_mfma_f32_16x16x32_bf16 v[6:9], v[96:99], v[144:147], v[6:9]
	v_mfma_f32_16x16x32_bf16 v[74:77], v[100:103], v[116:119], v[74:77]
	v_mfma_f32_16x16x32_bf16 v[58:61], v[108:111], v[116:119], v[58:61]
	v_mfma_f32_16x16x32_bf16 v[42:45], v[100:103], v[124:127], v[42:45]
	v_mfma_f32_16x16x32_bf16 v[34:37], v[108:111], v[124:127], v[34:37]
	v_mfma_f32_16x16x32_bf16 v[26:29], v[100:103], v[132:135], v[26:29]
	v_mfma_f32_16x16x32_bf16 v[18:21], v[108:111], v[132:135], v[18:21]
	v_mfma_f32_16x16x32_bf16 v[10:13], v[100:103], v[140:143], v[10:13]
	v_mfma_f32_16x16x32_bf16 v[2:5], v[108:111], v[140:143], v[2:5]
	v_mfma_f32_16x16x32_bf16 v[74:77], v[104:107], v[120:123], v[74:77]
	v_mfma_f32_16x16x32_bf16 v[58:61], v[112:115], v[120:123], v[58:61]
	v_mfma_f32_16x16x32_bf16 v[42:45], v[104:107], v[128:131], v[42:45]
	v_mfma_f32_16x16x32_bf16 v[34:37], v[112:115], v[128:131], v[34:37]
	v_mfma_f32_16x16x32_bf16 v[26:29], v[104:107], v[136:139], v[26:29]
	v_mfma_f32_16x16x32_bf16 v[18:21], v[112:115], v[136:139], v[18:21]
	v_mfma_f32_16x16x32_bf16 v[10:13], v[104:107], v[144:147], v[10:13]
	v_mfma_f32_16x16x32_bf16 v[2:5], v[112:115], v[144:147], v[2:5]
	s_setprio 0
	s_barrier
	s_add_i32 s27, s27, 1
	s_cmp_lt_u32 s27, 16
	s_cbranch_scc1 .LBB0_268
.Lst_done:
	s_cmpk_lt_u32 s15, 0x100
	s_cbranch_scc0 .LBB0_271
	s_barrier

.LBB0_786:
	v_mov_b32_e32 v39, v0
	v_lshl_add_u64 v[10:11], s[4:5], 0, v[38:39]
	v_mov_b32_e32 v35, v0
	v_lshl_add_u64 v[12:13], s[4:5], 0, v[34:35]
	v_mov_b32_e32 v41, v0
	s_add_i32 m0, s20, 0x18000
	v_lshl_add_u64 v[10:11], v[10:11], 0, s[76:77]
	v_lshl_add_u64 v[18:19], s[6:7], 0, v[40:41]
	v_mov_b32_e32 v37, v0
	s_waitcnt vmcnt(2)
	s_barrier
	global_load_lds_dwordx4 v[10:11], off
	v_lshl_add_u64 v[10:11], v[12:13], 0, s[76:77]
	s_add_i32 m0, s20, 0x1a000
	s_add_i32 s31, s20, 0x8000
	v_lshl_add_u64 v[20:21], s[6:7], 0, v[36:37]
	global_load_lds_dwordx4 v[10:11], off
	v_lshl_add_u64 v[10:11], v[18:19], 0, s[76:77]
	s_mov_b32 m0, s31
	s_add_i32 s34, s20, 0xa000
	v_lshl_add_u64 v[14:15], s[8:9], 0, v[38:39]
	global_load_lds_dwordx4 v[10:11], off
	v_lshl_add_u64 v[10:11], v[20:21], 0, s[76:77]
	s_mov_b32 m0, s34
	v_lshl_add_u64 v[16:17], s[8:9], 0, v[34:35]
	global_load_lds_dwordx4 v[10:11], off
	s_add_i32 m0, s20, 0x1c000
	v_lshl_add_u64 v[10:11], v[14:15], 0, s[76:77]
	global_load_lds_dwordx4 v[10:11], off
	v_lshl_add_u64 v[10:11], v[16:17], 0, s[76:77]
	s_add_i32 m0, s20, 0x1e000
	v_bfe_u32 v1, v5, 4, 2
	global_load_lds_dwordx4 v[10:11], off
	v_and_b32_e32 v9, 15, v5
	v_lshlrev_b32_e32 v22, 4, v1
	v_lshlrev_b32_e32 v5, 2, v5
	v_lshl_or_b32 v114, s15, 6, v9
	v_lshl_or_b32 v9, v9, 6, v22
	s_lshl_b32 s0, s15, 13
	v_and_b32_e32 v5, 32, v5
	v_bitop3_b32 v22, v9, s0, v5 bitop3:0xde
	s_lshl_b32 s0, s14, 5
	s_and_b32 s21, s0, 0x60
	s_lshl_b32 s0, s21, 7
	v_bitop3_b32 v54, v9, s0, v5 bitop3:0xde
	v_readlane_b32 s0, v254, 56
	s_add_i32 s35, s36, -2
	s_mul_i32 s0, s0, s1
	s_add_u32 s0, s10, s0
	s_addc_u32 s1, s11, 0
	s_add_u32 s0, s38, s0
	s_addc_u32 s1, s37, s1
	s_add_u32 s8, s0, 0x80
	v_add_u32_e32 v2, v4, v2
	s_waitcnt vmcnt(6)
	v_add_u32_e32 v5, v8, v6
	s_addc_u32 s9, s1, 0
	v_add_lshl_u32 v2, v2, v3, 1
	v_mov_b32_e32 v3, v0
	v_add_lshl_u32 v6, v5, v7, 1
	v_mov_b32_e32 v7, v0
	v_lshl_add_u64 v[52:53], s[8:9], 0, v[2:3]
	v_lshl_add_u64 v[50:51], s[8:9], 0, v[6:7]
	s_mov_b32 s14, 0
	s_mov_b64 s[8:9], 0
	v_add_u32_e32 v55, 0, v22
	s_barrier
	s_movk_i32 s8, 0x100
	s_lshl_b32 s9, s36, 7
	s_mov_b32 s14, 0
	v_add_u32_e32 v68, 0x10000, v54
	v_add_u32_e32 v69, 0x21c00, v54
	s_add_u32 s40, s4, s8
	s_addc_u32 s41, s5, 0
	s_add_u32 s42, s40, s12
	s_addc_u32 s43, s41, 0
	s_add_u32 s10, s6, s8
	s_addc_u32 s11, s7, 0
	s_addk_i32 s8, 0x80
	s_cmp_eq_u32 s8, s9
	s_cselect_b32 s8, 0, s8
	s_add_i32 m0, s20, 0xc000
	ds_read_b128 v[56:59], v68 offset:0
	ds_read_b128 v[60:63], v68 offset:1024
	ds_read_b128 v[64:67], v68 offset:2048
	ds_read_b128 v[74:77], v68 offset:3072
	global_load_lds_dwordx4 v38, s[40:41]
	s_add_i32 m0, s20, 0xe000
	ds_read_b128 v[116:119], v55 offset:0
	ds_read_b128 v[120:123], v55 offset:1024
	ds_read_b128 v[124:127], v55 offset:2048
	global_load_lds_dwordx4 v34, s[40:41]
	s_add_i32 m0, s20, 0x21c00
	ds_read_b128 v[128:131], v55 offset:3072
	ds_read_b128 v[132:135], v55 offset:4096
	ds_read_b128 v[136:139], v55 offset:5120
	global_load_lds_dwordx4 v38, s[42:43]
	s_add_i32 m0, s20, 0x23c00
	ds_read_b128 v[140:143], v55 offset:6144
	ds_read_b128 v[144:147], v55 offset:7168
	global_load_lds_dwordx4 v34, s[42:43]
	s_add_i32 m0, s20, 0x4000
	ds_read_b128 v[98:101], v68 offset:16384
	ds_read_b128 v[102:105], v68 offset:17408
	global_load_lds_dwordx4 v40, s[10:11]
	s_add_i32 m0, s20, 0x6000
	ds_read_b128 v[106:109], v68 offset:18432
	ds_read_b128 v[110:113], v68 offset:19456
	global_load_lds_dwordx4 v36, s[10:11]
	s_waitcnt vmcnt(6)
	s_waitcnt lgkmcnt(0)
	s_barrier
	s_setprio 1
	v_mfma_f32_16x16x32_bf16 v[94:97], v[56:59], v[116:119], 0
	v_mfma_f32_16x16x32_bf16 v[90:93], v[64:67], v[116:119], 0
	v_mfma_f32_16x16x32_bf16 v[78:81], v[56:59], v[124:127], 0
	s_add_u32 s40, s4, s8
	v_mfma_f32_16x16x32_bf16 v[70:73], v[64:67], v[124:127], 0
	s_addc_u32 s41, s5, 0
	v_mfma_f32_16x16x32_bf16 v[30:33], v[56:59], v[132:135], 0
	s_add_u32 s42, s40, s12
	v_mfma_f32_16x16x32_bf16 v[26:29], v[64:67], v[132:135], 0
	s_addc_u32 s43, s41, 0
	v_mfma_f32_16x16x32_bf16 v[14:17], v[56:59], v[140:143], 0
	s_add_u32 s10, s6, s8
	v_mfma_f32_16x16x32_bf16 v[10:13], v[64:67], v[140:143], 0
	s_addc_u32 s11, s7, 0
	v_mfma_f32_16x16x32_bf16 v[94:97], v[60:63], v[120:123], v[94:97]
	s_addk_i32 s8, 0x80
	v_mfma_f32_16x16x32_bf16 v[90:93], v[74:77], v[120:123], v[90:93]
	s_cmp_eq_u32 s8, s9
	v_mfma_f32_16x16x32_bf16 v[78:81], v[60:63], v[128:131], v[78:81]
	s_cselect_b32 s8, 0, s8
	v_mfma_f32_16x16x32_bf16 v[70:73], v[74:77], v[128:131], v[70:73]
	v_mfma_f32_16x16x32_bf16 v[30:33], v[60:63], v[136:139], v[30:33]
	v_mfma_f32_16x16x32_bf16 v[26:29], v[74:77], v[136:139], v[26:29]
	v_mfma_f32_16x16x32_bf16 v[14:17], v[60:63], v[144:147], v[14:17]
	v_mfma_f32_16x16x32_bf16 v[10:13], v[74:77], v[144:147], v[10:13]
	v_mfma_f32_16x16x32_bf16 v[86:89], v[98:101], v[116:119], 0
	v_mfma_f32_16x16x32_bf16 v[82:85], v[106:109], v[116:119], 0
	v_mfma_f32_16x16x32_bf16 v[46:49], v[98:101], v[124:127], 0
	v_mfma_f32_16x16x32_bf16 v[42:45], v[106:109], v[124:127], 0
	v_mfma_f32_16x16x32_bf16 v[22:25], v[98:101], v[132:135], 0
	v_mfma_f32_16x16x32_bf16 v[18:21], v[106:109], v[132:135], 0
	v_mfma_f32_16x16x32_bf16 v[6:9], v[98:101], v[140:143], 0
	v_mfma_f32_16x16x32_bf16 v[2:5], v[106:109], v[140:143], 0
	v_mfma_f32_16x16x32_bf16 v[86:89], v[102:105], v[120:123], v[86:89]
	v_mfma_f32_16x16x32_bf16 v[82:85], v[110:113], v[120:123], v[82:85]
	v_mfma_f32_16x16x32_bf16 v[46:49], v[102:105], v[128:131], v[46:49]
	v_mfma_f32_16x16x32_bf16 v[42:45], v[110:113], v[128:131], v[42:45]
	v_mfma_f32_16x16x32_bf16 v[22:25], v[102:105], v[136:139], v[22:25]
	v_mfma_f32_16x16x32_bf16 v[18:21], v[110:113], v[136:139], v[18:21]
	v_mfma_f32_16x16x32_bf16 v[6:9], v[102:105], v[144:147], v[6:9]
	v_mfma_f32_16x16x32_bf16 v[2:5], v[110:113], v[144:147], v[2:5]
	s_setprio 0
	s_barrier
	s_add_i32 s14, s14, 1
.LBB0_787:
	s_add_i32 m0, s20, 0x10000
	ds_read_b128 v[56:59], v68 offset:32768
	ds_read_b128 v[60:63], v68 offset:33792
	ds_read_b128 v[64:67], v68 offset:34816
	ds_read_b128 v[74:77], v68 offset:35840
	global_load_lds_dwordx4 v38, s[40:41]
	s_add_i32 m0, s20, 0x12000
	ds_read_b128 v[116:119], v55 offset:32768
	ds_read_b128 v[120:123], v55 offset:33792
	ds_read_b128 v[124:127], v55 offset:34816
	global_load_lds_dwordx4 v34, s[40:41]
	s_add_i32 m0, s20, 0x14000
	ds_read_b128 v[128:131], v55 offset:35840
	ds_read_b128 v[132:135], v55 offset:36864
	ds_read_b128 v[136:139], v55 offset:37888
	global_load_lds_dwordx4 v38, s[42:43]
	s_add_i32 m0, s20, 0x16000
	ds_read_b128 v[140:143], v55 offset:38912
	ds_read_b128 v[144:147], v55 offset:39936
	global_load_lds_dwordx4 v34, s[42:43]
	s_add_i32 m0, s20, 0x0
	ds_read_b128 v[98:101], v68 offset:49152
	ds_read_b128 v[102:105], v68 offset:50176
	global_load_lds_dwordx4 v40, s[10:11]
	s_add_i32 m0, s20, 0x2000
	ds_read_b128 v[106:109], v68 offset:51200
	ds_read_b128 v[110:113], v68 offset:52224
	global_load_lds_dwordx4 v36, s[10:11]
	s_waitcnt vmcnt(6)
	s_waitcnt lgkmcnt(0)
	s_barrier
	s_setprio 1
	v_mfma_f32_16x16x32_bf16 v[94:97], v[56:59], v[116:119], v[94:97]
	v_mfma_f32_16x16x32_bf16 v[90:93], v[64:67], v[116:119], v[90:93]
	v_mfma_f32_16x16x32_bf16 v[78:81], v[56:59], v[124:127], v[78:81]
	s_add_u32 s40, s4, s8
	v_mfma_f32_16x16x32_bf16 v[70:73], v[64:67], v[124:127], v[70:73]
	s_addc_u32 s41, s5, 0
	v_mfma_f32_16x16x32_bf16 v[30:33], v[56:59], v[132:135], v[30:33]
	s_add_u32 s42, s40, s12
	v_mfma_f32_16x16x32_bf16 v[26:29], v[64:67], v[132:135], v[26:29]
	s_addc_u32 s43, s41, 0
	v_mfma_f32_16x16x32_bf16 v[14:17], v[56:59], v[140:143], v[14:17]
	s_add_u32 s10, s6, s8
	v_mfma_f32_16x16x32_bf16 v[10:13], v[64:67], v[140:143], v[10:13]
	s_addc_u32 s11, s7, 0
	v_mfma_f32_16x16x32_bf16 v[94:97], v[60:63], v[120:123], v[94:97]
	s_addk_i32 s8, 0x80
	v_mfma_f32_16x16x32_bf16 v[90:93], v[74:77], v[120:123], v[90:93]
	s_cmp_eq_u32 s8, s9
	v_mfma_f32_16x16x32_bf16 v[78:81], v[60:63], v[128:131], v[78:81]
	s_cselect_b32 s8, 0, s8
	v_mfma_f32_16x16x32_bf16 v[70:73], v[74:77], v[128:131], v[70:73]
	v_mfma_f32_16x16x32_bf16 v[30:33], v[60:63], v[136:139], v[30:33]
	v_mfma_f32_16x16x32_bf16 v[26:29], v[74:77], v[136:139], v[26:29]
	v_mfma_f32_16x16x32_bf16 v[14:17], v[60:63], v[144:147], v[14:17]
	v_mfma_f32_16x16x32_bf16 v[10:13], v[74:77], v[144:147], v[10:13]
	v_mfma_f32_16x16x32_bf16 v[86:89], v[98:101], v[116:119], v[86:89]
	v_mfma_f32_16x16x32_bf16 v[82:85], v[106:109], v[116:119], v[82:85]
	v_mfma_f32_16x16x32_bf16 v[46:49], v[98:101], v[124:127], v[46:49]
	v_mfma_f32_16x16x32_bf16 v[42:45], v[106:109], v[124:127], v[42:45]
	v_mfma_f32_16x16x32_bf16 v[22:25], v[98:101], v[132:135], v[22:25]
	v_mfma_f32_16x16x32_bf16 v[18:21], v[106:109], v[132:135], v[18:21]
	v_mfma_f32_16x16x32_bf16 v[6:9], v[98:101], v[140:143], v[6:9]
	v_mfma_f32_16x16x32_bf16 v[2:5], v[106:109], v[140:143], v[2:5]
	v_mfma_f32_16x16x32_bf16 v[86:89], v[102:105], v[120:123], v[86:89]
	v_mfma_f32_16x16x32_bf16 v[82:85], v[110:113], v[120:123], v[82:85]
	v_mfma_f32_16x16x32_bf16 v[46:49], v[102:105], v[128:131], v[46:49]
	v_mfma_f32_16x16x32_bf16 v[42:45], v[110:113], v[128:131], v[42:45]
	v_mfma_f32_16x16x32_bf16 v[22:25], v[102:105], v[136:139], v[22:25]
	v_mfma_f32_16x16x32_bf16 v[18:21], v[110:113], v[136:139], v[18:21]
	v_mfma_f32_16x16x32_bf16 v[6:9], v[102:105], v[144:147], v[6:9]
	v_mfma_f32_16x16x32_bf16 v[2:5], v[110:113], v[144:147], v[2:5]
	s_setprio 0
	s_barrier
	s_add_i32 s14, s14, 1
	s_cmp_ge_u32 s14, s36
	s_cbranch_scc1 .Lrt_done
	s_add_i32 m0, s20, 0x18000
	ds_read_b128 v[56:59], v54 offset:49152
	ds_read_b128 v[60:63], v54 offset:50176
	ds_read_b128 v[64:67], v54 offset:51200
	ds_read_b128 v[74:77], v54 offset:52224
	global_load_lds_dwordx4 v38, s[40:41]
	s_add_i32 m0, s20, 0x1a000
	ds_read_b128 v[116:119], v55 offset:16384
	ds_read_b128 v[120:123], v55 offset:17408
	ds_read_b128 v[124:127], v55 offset:18432
	global_load_lds_dwordx4 v34, s[40:41]
	s_add_i32 m0, s20, 0x1c000
	ds_read_b128 v[128:131], v55 offset:19456
	ds_read_b128 v[132:135], v55 offset:20480
	ds_read_b128 v[136:139], v55 offset:21504
	global_load_lds_dwordx4 v38, s[42:43]
	s_add_i32 m0, s20, 0x1e000
	ds_read_b128 v[140:143], v55 offset:22528
	ds_read_b128 v[144:147], v55 offset:23552
	global_load_lds_dwordx4 v34, s[42:43]
	s_add_i32 m0, s20, 0x8000
	ds_read_b128 v[98:101], v69 offset:0
	ds_read_b128 v[102:105], v69 offset:1024
	global_load_lds_dwordx4 v40, s[10:11]
	s_add_i32 m0, s20, 0xa000
	ds_read_b128 v[106:109], v69 offset:2048
	ds_read_b128 v[110:113], v69 offset:3072
	global_load_lds_dwordx4 v36, s[10:11]
	s_waitcnt vmcnt(6)
	s_waitcnt lgkmcnt(0)
	s_barrier
	s_setprio 1
	v_mfma_f32_16x16x32_bf16 v[94:97], v[56:59], v[116:119], v[94:97]
	v_mfma_f32_16x16x32_bf16 v[90:93], v[64:67], v[116:119], v[90:93]
	v_mfma_f32_16x16x32_bf16 v[78:81], v[56:59], v[124:127], v[78:81]
	s_add_u32 s40, s4, s8
	v_mfma_f32_16x16x32_bf16 v[70:73], v[64:67], v[124:127], v[70:73]
	s_addc_u32 s41, s5, 0
	v_mfma_f32_16x16x32_bf16 v[30:33], v[56:59], v[132:135], v[30:33]
	s_add_u32 s42, s40, s12
	v_mfma_f32_16x16x32_bf16 v[26:29], v[64:67], v[132:135], v[26:29]
	s_addc_u32 s43, s41, 0
	v_mfma_f32_16x16x32_bf16 v[14:17], v[56:59], v[140:143], v[14:17]
	s_add_u32 s10, s6, s8
	v_mfma_f32_16x16x32_bf16 v[10:13], v[64:67], v[140:143], v[10:13]
	s_addc_u32 s11, s7, 0
	v_mfma_f32_16x16x32_bf16 v[94:97], v[60:63], v[120:123], v[94:97]
	s_addk_i32 s8, 0x80
	v_mfma_f32_16x16x32_bf16 v[90:93], v[74:77], v[120:123], v[90:93]
	s_cmp_eq_u32 s8, s9
	v_mfma_f32_16x16x32_bf16 v[78:81], v[60:63], v[128:131], v[78:81]
	s_cselect_b32 s8, 0, s8
	v_mfma_f32_16x16x32_bf16 v[70:73], v[74:77], v[128:131], v[70:73]
	v_mfma_f32_16x16x32_bf16 v[30:33], v[60:63], v[136:139], v[30:33]
	v_mfma_f32_16x16x32_bf16 v[26:29], v[74:77], v[136:139], v[26:29]
	v_mfma_f32_16x16x32_bf16 v[14:17], v[60:63], v[144:147], v[14:17]
	v_mfma_f32_16x16x32_bf16 v[10:13], v[74:77], v[144:147], v[10:13]
	v_mfma_f32_16x16x32_bf16 v[86:89], v[98:101], v[116:119], v[86:89]
	v_mfma_f32_16x16x32_bf16 v[82:85], v[106:109], v[116:119], v[82:85]
	v_mfma_f32_16x16x32_bf16 v[46:49], v[98:101], v[124:127], v[46:49]
	v_mfma_f32_16x16x32_bf16 v[42:45], v[106:109], v[124:127], v[42:45]
	v_mfma_f32_16x16x32_bf16 v[22:25], v[98:101], v[132:135], v[22:25]
	v_mfma_f32_16x16x32_bf16 v[18:21], v[106:109], v[132:135], v[18:21]
	v_mfma_f32_16x16x32_bf16 v[6:9], v[98:101], v[140:143], v[6:9]
	v_mfma_f32_16x16x32_bf16 v[2:5], v[106:109], v[140:143], v[2:5]
	v_mfma_f32_16x16x32_bf16 v[86:89], v[102:105], v[120:123], v[86:89]
	v_mfma_f32_16x16x32_bf16 v[82:85], v[110:113], v[120:123], v[82:85]
	v_mfma_f32_16x16x32_bf16 v[46:49], v[102:105], v[128:131], v[46:49]
	v_mfma_f32_16x16x32_bf16 v[42:45], v[110:113], v[128:131], v[42:45]
	v_mfma_f32_16x16x32_bf16 v[22:25], v[102:105], v[136:139], v[22:25]
	v_mfma_f32_16x16x32_bf16 v[18:21], v[110:113], v[136:139], v[18:21]
	v_mfma_f32_16x16x32_bf16 v[6:9], v[102:105], v[144:147], v[6:9]
	v_mfma_f32_16x16x32_bf16 v[2:5], v[110:113], v[144:147], v[2:5]
	s_setprio 0
	s_barrier
	s_add_i32 s14, s14, 1
	s_cmp_ge_u32 s14, s36
	s_cbranch_scc1 .Lrt_done
	s_add_i32 m0, s20, 0xc000
	ds_read_b128 v[56:59], v68 offset:0
	ds_read_b128 v[60:63], v68 offset:1024
	ds_read_b128 v[64:67], v68 offset:2048
	ds_read_b128 v[74:77], v68 offset:3072
	global_load_lds_dwordx4 v38, s[40:41]
	s_add_i32 m0, s20, 0xe000
	ds_read_b128 v[116:119], v55 offset:0
	ds_read_b128 v[120:123], v55 offset:1024
	ds_read_b128 v[124:127], v55 offset:2048
	global_load_lds_dwordx4 v34, s[40:41]
	s_add_i32 m0, s20, 0x21c00
	ds_read_b128 v[128:131], v55 offset:3072
	ds_read_b128 v[132:135], v55 offset:4096
	ds_read_b128 v[136:139], v55 offset:5120
	global_load_lds_dwordx4 v38, s[42:43]
	s_add_i32 m0, s20, 0x23c00
	ds_read_b128 v[140:143], v55 offset:6144
	ds_read_b128 v[144:147], v55 offset:7168
	global_load_lds_dwordx4 v34, s[42:43]
	s_add_i32 m0, s20, 0x4000
	ds_read_b128 v[98:101], v68 offset:16384
	ds_read_b128 v[102:105], v68 offset:17408
	global_load_lds_dwordx4 v40, s[10:11]
	s_add_i32 m0, s20, 0x6000
	ds_read_b128 v[106:109], v68 offset:18432
	ds_read_b128 v[110:113], v68 offset:19456
	global_load_lds_dwordx4 v36, s[10:11]
	s_waitcnt vmcnt(6)
	s_waitcnt lgkmcnt(0)
	s_barrier
	s_setprio 1
	v_mfma_f32_16x16x32_bf16 v[94:97], v[56:59], v[116:119], v[94:97]
	v_mfma_f32_16x16x32_bf16 v[90:93], v[64:67], v[116:119], v[90:93]
	v_mfma_f32_16x16x32_bf16 v[78:81], v[56:59], v[124:127], v[78:81]
	s_add_u32 s40, s4, s8
	v_mfma_f32_16x16x32_bf16 v[70:73], v[64:67], v[124:127], v[70:73]
	s_addc_u32 s41, s5, 0
	v_mfma_f32_16x16x32_bf16 v[30:33], v[56:59], v[132:135], v[30:33]
	s_add_u32 s42, s40, s12
	v_mfma_f32_16x16x32_bf16 v[26:29], v[64:67], v[132:135], v[26:29]
	s_addc_u32 s43, s41, 0
	v_mfma_f32_16x16x32_bf16 v[14:17], v[56:59], v[140:143], v[14:17]
	s_add_u32 s10, s6, s8
	v_mfma_f32_16x16x32_bf16 v[10:13], v[64:67], v[140:143], v[10:13]
	s_addc_u32 s11, s7, 0
	v_mfma_f32_16x16x32_bf16 v[94:97], v[60:63], v[120:123], v[94:97]
	s_addk_i32 s8, 0x80
	v_mfma_f32_16x16x32_bf16 v[90:93], v[74:77], v[120:123], v[90:93]
	s_cmp_eq_u32 s8, s9
	v_mfma_f32_16x16x32_bf16 v[78:81], v[60:63], v[128:131], v[78:81]
	s_cselect_b32 s8, 0, s8
	v_mfma_f32_16x16x32_bf16 v[70:73], v[74:77], v[128:131], v[70:73]
	v_mfma_f32_16x16x32_bf16 v[30:33], v[60:63], v[136:139], v[30:33]
	v_mfma_f32_16x16x32_bf16 v[26:29], v[74:77], v[136:139], v[26:29]
	v_mfma_f32_16x16x32_bf16 v[14:17], v[60:63], v[144:147], v[14:17]
	v_mfma_f32_16x16x32_bf16 v[10:13], v[74:77], v[144:147], v[10:13]
	v_mfma_f32_16x16x32_bf16 v[86:89], v[98:101], v[116:119], v[86:89]
	v_mfma_f32_16x16x32_bf16 v[82:85], v[106:109], v[116:119], v[82:85]
	v_mfma_f32_16x16x32_bf16 v[46:49], v[98:101], v[124:127], v[46:49]
	v_mfma_f32_16x16x32_bf16 v[42:45], v[106:109], v[124:127], v[42:45]
	v_mfma_f32_16x16x32_bf16 v[22:25], v[98:101], v[132:135], v[22:25]
	v_mfma_f32_16x16x32_bf16 v[18:21], v[106:109], v[132:135], v[18:21]
	v_mfma_f32_16x16x32_bf16 v[6:9], v[98:101], v[140:143], v[6:9]
	v_mfma_f32_16x16x32_bf16 v[2:5], v[106:109], v[140:143], v[2:5]
	v_mfma_f32_16x16x32_bf16 v[86:89], v[102:105], v[120:123], v[86:89]
	v_mfma_f32_16x16x32_bf16 v[82:85], v[110:113], v[120:123], v[82:85]
	v_mfma_f32_16x16x32_bf16 v[46:49], v[102:105], v[128:131], v[46:49]
	v_mfma_f32_16x16x32_bf16 v[42:45], v[110:113], v[128:131], v[42:45]
	v_mfma_f32_16x16x32_bf16 v[22:25], v[102:105], v[136:139], v[22:25]
	v_mfma_f32_16x16x32_bf16 v[18:21], v[110:113], v[136:139], v[18:21]
	v_mfma_f32_16x16x32_bf16 v[6:9], v[102:105], v[144:147], v[6:9]
	v_mfma_f32_16x16x32_bf16 v[2:5], v[110:113], v[144:147], v[2:5]
	s_setprio 0
	s_barrier
	s_add_i32 s14, s14, 1
	s_cmp_lt_u32 s14, s36
	s_cbranch_scc1 .LBB0_787
